# plus attention phase: waves 4-7 start each item half a tile late so SIMD partners alternate MFMA and softmax
# speedup vs baseline: 1.0181x; 1.0181x over previous
; __global__ void __launch_bounds__(512, 2) fwd_mega(Args args) {
;     ...
;             for (;;) {
;                 __syncthreads();
;                 if (tid == 0) *qslot = (int)atomicAdd(ctr + 16 + l * 8 + (bx & 7), 1u);
;                 __syncthreads();
;                 const int v = *qslot;
;                 if (v >= 68) break;
;                 int ln = threadIdx.x & 63; asm volatile("" : "+v"(ln));
;                 const int xg = bx & 7;
;                 int b = 0, c = 0, s = -1;
;                 if (v < 48) { b = 2 * xg + v / 24; c = 8 + v % 24; }
;                 else if (v < 56) { const int k = v - 48; c = 7 - (k >> 1); b = 2 * xg + (k & 1); }
;                 else if (v < 60) { s = 4 * xg + (v - 56); }
;                 else { const int k = v - 60; c = 3 - (k >> 1); b = 2 * xg + (k & 1); }
.LBB0_538:
	s_or_b64 exec, exec, s[2:3]
	v_mov_b32_e32 v0, s77
	s_waitcnt lgkmcnt(0)
	s_barrier
	ds_read_b32 v0, v0
	s_movk_i32 s2, 0x43
	s_waitcnt lgkmcnt(0)
	v_cmp_lt_i32_e32 vcc, s2, v0
	v_readfirstlane_b32 s4, v0
	s_mov_b64 s[2:3], -1
	s_cbranch_vccnz .LBB0_533
	v_and_b32_e32 v212, 63, v191
	v_readfirstlane_b32 s98, v191
	s_nop 3
	s_cmp_lt_u32 s98, 0x100
	s_cbranch_scc1 .Lattn_nostag
	s_sleep 20
.Lattn_nostag:
	s_cmp_gt_i32 s4, 47
	s_cbranch_scc0 .LBB0_549
	s_cmp_gt_u32 s4, 55
	s_cbranch_scc0 .LBB0_546
	s_cmp_gt_u32 s4, 59
	s_cbranch_scc0 .LBB0_543
	s_sub_i32 s2, s4, 60
	s_lshr_b32 s2, s2, 1
	s_sub_i32 s7, 3, s2
	s_and_b32 s2, s4, 1
	v_readlane_b32 s3, v255, 2
	s_or_b32 s5, s2, s3
	s_mov_b64 s[2:3], 0
